# scan: L2 touch-prefetch, each V wave touches one dword per 128B line of its dvb's quarter of the W/QD/KDT/ATT/UT data 8 steps ahead so the real loads hit L2
# speedup vs baseline: 1.0064x; 1.0064x over previous
.LBB0_652:
	s_andn2_b64 vcc, exec, s[0:1]
	s_cbranch_vccnz .LBB0_704
	v_and_b32_e32 v14, 63, v206
	v_lshrrev_b32_e32 v15, 6, v206
	v_and_b32_e32 v64, 15, v14
	v_readfirstlane_b32 s11, v15
	v_lshrrev_b32_e32 v65, 4, v14
	v_lshlrev_b32_e32 v66, 2, v206
	ds_write_b32 v66, v0
	ds_write_b32 v66, v0 offset:2048
	ds_write_b32 v66, v0 offset:4096
	ds_write_b32 v66, v0 offset:6144
	ds_write_b32 v66, v0 offset:8192
	s_and_b32 s12, s11, 3
	s_and_b32 s13, s72, 7
	s_lshr_b32 s14, s72, 5
	s_bfe_u32 s15, s72, 0x20003
	s_lshl_b32 s16, s14, 3
	s_add_u32 s16, s16, s13
	s_lshl_b32 s17, s16, 21
	v_and_b32_e32 v4, 31, v14
	s_lshl_b32 s18, s15, 5
	v_add_u32_e32 v4, s18, v4
	v_lshlrev_b32_e32 v5, 7, v4
	s_and_b32 s18, s11, 3
	s_lshl_b32 s18, s18, 25
	s_add_u32 s18, s18, 0x11800000
	s_add_u32 s18, s18, s17
	v_add_u32_e32 v5, s18, v5
	v_mov_b32_e32 v6, 0x4000
	v_and_b32_e32 v4, 15, v14
	s_lshl_b32 s18, s15, 4
	v_add_u32_e32 v4, s18, v4
	v_lshlrev_b32_e32 v4, 7, v4
	s_lshr_b32 s18, s17, 1
	s_add_u32 s18, s18, 0x19800000
	v_add_u32_e32 v4, s18, v4
	v_cmp_lt_u32_e32 vcc, 31, v14
	s_nop 3
	s_cmp_eq_u32 s11, 3
	s_cselect_b64 s[18:19], vcc, 0
	v_mov_b32_e32 v7, 0x2000
	v_cndmask_b32_e64 v5, v5, v4, s[18:19]
	v_cndmask_b32_e64 v6, v6, v7, s[18:19]
	s_mov_b32 s18, 0x13800000
	s_cmp_lt_u32 s11, 4
	s_cselect_b32 s18, 0x11800000, s18
	s_add_u32 s18, s18, s17
	s_lshl_b32 s19, s12, 12
	s_add_u32 s18, s18, s19
	s_add_u32 s0, s70, s18
	s_addc_u32 s1, s71, 0
	s_lshl_b32 s19, s11, 11
	s_add_u32 s18, s17, s19
	s_add_u32 s18, s18, 0x15800000
	s_add_u32 s4, s70, s18
	s_addc_u32 s5, s71, 0
	s_lshl_b32 s18, s16, 9
	s_add_u32 s18, s18, 0x11500000
	s_add_u32 s6, s70, s18
	s_addc_u32 s7, s71, 0
	s_lshl_b32 s18, s15, 12
	s_lshl_b32 s19, s12, 9
	s_add_u32 s18, s18, s19
	s_add_u32 s18, s18, s17
	s_add_u32 s18, s18, 0x17800000
	s_lshl_b32 s19, s16, 20
	s_lshl_b32 s20, s12, 11
	s_add_u32 s19, s19, s20
	s_add_u32 s19, s19, 0x19800000
	s_cmp_lt_u32 s11, 4
	s_cselect_b32 s18, s18, s19
	s_add_u32 s2, s70, s18
	s_addc_u32 s3, s71, 0
	s_lshl_b32 s18, s14, 24
	s_lshl_b32 s19, s12, 15
	s_add_u32 s18, s18, s19
	s_lshl_b32 s19, s13, 8
	s_add_u32 s18, s18, s19
	s_lshl_b32 s19, s15, 6
	s_add_u32 s18, s18, s19
	s_add_u32 s18, s18, 0xb400000
	s_add_u32 s8, s70, s18
	s_addc_u32 s9, s71, 0
	v_lshlrev_b32_e32 v1, 4, v14
	v_mov_b32_e32 v3, 0
	v_mul_u32_u24_e32 v8, 0x110, v64
	v_mul_u32_u24_e32 v9, 0x90, v64
	v_lshl_add_u32 v11, v65, 3, v8
	v_lshl_add_u32 v10, v65, 3, v9
	v_lshl_add_u32 v8, v65, 4, v8
	v_lshl_add_u32 v9, v65, 4, v9
	s_lshl_b32 s18, s11, 5
	v_add_u32_e32 v11, s18, v11
	s_lshl_b32 s18, s12, 5
	v_add_u32_e32 v10, s18, v10
	s_mul_i32 s18, s12, 0x500
	s_add_u32 s18, s18, 0x5800
	v_mul_u32_u24_e32 v13, 0x140, v65
	v_lshl_add_u32 v13, v64, 1, v13
	v_add_u32_e32 v13, s18, v13
	v_lshrrev_b32_e32 v67, 2, v14
	v_and_b32_e32 v68, 3, v14
	v_mul_u32_u24_e32 v172, 0x50, v67
	v_lshl_add_u32 v172, v68, 4, v172
	v_add_u32_e32 v172, s18, v172
	v_lshlrev_b32_e32 v12, 11, v67
	v_lshl_add_u32 v12, v68, 4, v12
	v_mov_b32_e32 v16, 0
	v_mov_b32_e32 v17, 0
	v_mov_b32_e32 v18, 0
	v_mov_b32_e32 v19, 0
	v_mov_b32_e32 v20, 0
	v_mov_b32_e32 v21, 0
	v_mov_b32_e32 v22, 0
	v_mov_b32_e32 v23, 0
	s_cmp_lt_u32 s11, 4
	s_waitcnt lgkmcnt(0)
	s_barrier
	s_cbranch_scc0 .Lscan_O_path
	v_lshlrev_b32_e32 v2, 3, v14
	global_load_dwordx4 v[72:75], v1, s[0:1]
	global_load_dwordx4 v[76:79], v1, s[0:1] offset:1024
	global_load_dwordx4 v[80:83], v1, s[0:1] offset:2048
	global_load_dwordx4 v[84:87], v1, s[0:1] offset:3072
	global_load_dwordx2 v[88:89], v2, s[2:3]
	global_load_dwordx2 v[90:91], v2, s[2:3] offset:2048
	global_load_dwordx4 v[96:99], v1, s[4:5]
	global_load_dwordx4 v[100:103], v1, s[4:5] offset:1024
	global_load_dword v184, v3, s[6:7]
	v_add_u32_e32 v1, 0x4000, v1
	v_add_u32_e32 v2, 0x4000, v2
	v_add_u32_e32 v3, 4, v3
	global_load_dwordx4 v[104:107], v1, s[0:1]
	global_load_dwordx4 v[108:111], v1, s[0:1] offset:1024
	global_load_dwordx4 v[112:115], v1, s[0:1] offset:2048
	global_load_dwordx4 v[116:119], v1, s[0:1] offset:3072
	global_load_dwordx2 v[120:121], v2, s[2:3]
	global_load_dwordx2 v[122:123], v2, s[2:3] offset:2048
	global_load_dwordx4 v[128:131], v1, s[4:5]
	global_load_dwordx4 v[132:135], v1, s[4:5] offset:1024
	global_load_dword v185, v3, s[6:7]
	v_add_u32_e32 v1, 0x4000, v1
	v_add_u32_e32 v2, 0x4000, v2
	v_add_u32_e32 v3, 4, v3
	global_load_dwordx4 v[136:139], v1, s[0:1]
	global_load_dwordx4 v[140:143], v1, s[0:1] offset:1024
	global_load_dwordx4 v[144:147], v1, s[0:1] offset:2048
	global_load_dwordx4 v[148:151], v1, s[0:1] offset:3072
	global_load_dwordx2 v[188:189], v2, s[2:3]
	global_load_dwordx2 v[190:191], v2, s[2:3] offset:2048
	global_load_dwordx4 v[196:199], v1, s[4:5]
	global_load_dwordx4 v[200:203], v1, s[4:5] offset:1024
	global_load_dword v186, v3, s[6:7]
	v_add_u32_e32 v1, 0x4000, v1
	v_add_u32_e32 v2, 0x4000, v2
	v_add_u32_e32 v3, 4, v3
	global_load_dword v4, v5, s[70:71]
	v_add_u32_e32 v5, v6, v5
	global_load_dword v4, v5, s[70:71]
	v_add_u32_e32 v5, v6, v5
	global_load_dword v4, v5, s[70:71]
	v_add_u32_e32 v5, v6, v5
	global_load_dword v4, v5, s[70:71]
	v_add_u32_e32 v5, v6, v5
	global_load_dword v4, v5, s[70:71]
	v_add_u32_e32 v5, v6, v5
	global_load_dword v4, v5, s[70:71]
	v_add_u32_e32 v5, v6, v5
	global_load_dword v4, v5, s[70:71]
	v_add_u32_e32 v5, v6, v5
	global_load_dword v4, v5, s[70:71]
	v_add_u32_e32 v5, v6, v5
	s_waitcnt vmcnt(0)
	s_movk_i32 s10, 32
.Lscan_V_loop:
	s_waitcnt vmcnt(26)
	ds_read_b128 v[32:35], v8 offset:0
	ds_read_b128 v[36:39], v8 offset:4352
	ds_read_b128 v[40:43], v8 offset:64
	ds_read_b128 v[44:47], v8 offset:4416
	ds_read_b128 v[48:51], v8 offset:128
	ds_read_b128 v[52:55], v8 offset:4480
	ds_read_b128 v[56:59], v8 offset:192
	ds_read_b128 v[60:63], v8 offset:4544
	global_load_dwordx4 v[216:219], v1, s[0:1]
	global_load_dwordx4 v[220:223], v1, s[0:1] offset:1024
	s_waitcnt vmcnt(23)
	v_mul_f32_e32 v16, v184, v16
	v_mul_f32_e32 v17, v184, v17
	v_mul_f32_e32 v18, v184, v18
	v_mul_f32_e32 v19, v184, v19
	global_load_dwordx4 v[224:227], v1, s[0:1] offset:2048
	v_mul_f32_e32 v20, v184, v20
	v_mul_f32_e32 v21, v184, v21
	v_mul_f32_e32 v22, v184, v22
	v_mul_f32_e32 v23, v184, v23
	v_lshlrev_b32_e32 v64, 16, v88
	v_and_b32_e32 v65, 0xffff0000, v88
	v_lshlrev_b32_e32 v66, 16, v89
	v_and_b32_e32 v67, 0xffff0000, v89
	v_lshlrev_b32_e32 v68, 16, v90
	v_and_b32_e32 v69, 0xffff0000, v90
	v_lshlrev_b32_e32 v70, 16, v91
	v_and_b32_e32 v71, 0xffff0000, v91
	global_load_dwordx4 v[228:231], v1, s[0:1] offset:3072
	s_waitcnt lgkmcnt(6)
	v_mfma_f32_16x16x32_bf16 v[24:27], v[72:75], v[32:35], 0
	v_mfma_f32_16x16x32_bf16 v[28:31], v[72:75], v[36:39], 0
	global_load_dwordx2 v[232:233], v2, s[2:3]
	s_waitcnt lgkmcnt(4)
	v_mfma_f32_16x16x32_bf16 v[24:27], v[76:79], v[40:43], v[24:27]
	v_mfma_f32_16x16x32_bf16 v[28:31], v[76:79], v[44:47], v[28:31]
	global_load_dwordx2 v[234:235], v2, s[2:3] offset:2048
	s_waitcnt lgkmcnt(2)
	v_mfma_f32_16x16x32_bf16 v[24:27], v[80:83], v[48:51], v[24:27]
	v_mfma_f32_16x16x32_bf16 v[28:31], v[80:83], v[52:55], v[28:31]
	global_load_dwordx4 v[240:243], v1, s[4:5]
	s_waitcnt lgkmcnt(0)
	v_mfma_f32_16x16x32_bf16 v[24:27], v[84:87], v[56:59], v[24:27]
	v_mfma_f32_16x16x32_bf16 v[28:31], v[84:87], v[60:63], v[28:31]
	global_load_dwordx4 v[244:247], v1, s[4:5] offset:1024
	global_load_dword v187, v3, s[6:7]
	global_load_dword v4, v5, s[70:71]
	v_add_u32_e32 v5, v6, v5
	v_add_u32_e32 v1, 0x4000, v1
	v_add_u32_e32 v2, 0x4000, v2
	v_add_u32_e32 v3, 4, v3
	s_nop 2
	v_sub_f32_e32 v64, v64, v24
	v_sub_f32_e32 v65, v65, v25
	v_sub_f32_e32 v66, v66, v26
	v_sub_f32_e32 v67, v67, v27
	v_sub_f32_e32 v68, v68, v28
	v_sub_f32_e32 v69, v69, v29
	v_sub_f32_e32 v70, v70, v30
	v_sub_f32_e32 v71, v71, v31
	v_cvt_pk_bf16_f32 v64, v64, v65
	v_cvt_pk_bf16_f32 v65, v66, v67
	v_cvt_pk_bf16_f32 v68, v68, v69
	v_cvt_pk_bf16_f32 v69, v70, v71
	ds_write_b64 v10, v[64:65] offset:17408
	ds_write_b64 v10, v[68:69] offset:19712
	s_waitcnt lgkmcnt(0)
	s_barrier
	ds_read_b128 v[32:35], v9 offset:17408
	ds_read_b128 v[36:39], v9 offset:19712
	ds_read_b128 v[40:43], v9 offset:17472
	ds_read_b128 v[44:47], v9 offset:19776
	s_waitcnt lgkmcnt(2)
	v_mfma_f32_16x16x32_bf16 v[16:19], v[96:99], v[32:35], v[16:19]
	v_mfma_f32_16x16x32_bf16 v[20:23], v[96:99], v[36:39], v[20:23]
	s_waitcnt lgkmcnt(0)
	v_mfma_f32_16x16x32_bf16 v[16:19], v[100:103], v[40:43], v[16:19]
	v_mfma_f32_16x16x32_bf16 v[20:23], v[100:103], v[44:47], v[20:23]
	s_nop 7
	v_cvt_pk_bf16_f32 v64, v16, v17
	v_cvt_pk_bf16_f32 v65, v18, v19
	v_cvt_pk_bf16_f32 v66, v20, v21
	v_cvt_pk_bf16_f32 v67, v22, v23
	ds_write_b64 v11, v[64:65] offset:8704
	ds_write_b64 v11, v[66:67] offset:13056
	s_waitcnt lgkmcnt(0)
	s_barrier
	s_waitcnt vmcnt(26)
	ds_read_b128 v[32:35], v8 offset:8704
	ds_read_b128 v[36:39], v8 offset:13056
	ds_read_b128 v[40:43], v8 offset:8768
	ds_read_b128 v[44:47], v8 offset:13120
	ds_read_b128 v[48:51], v8 offset:8832
	ds_read_b128 v[52:55], v8 offset:13184
	ds_read_b128 v[56:59], v8 offset:8896
	ds_read_b128 v[60:63], v8 offset:13248
	global_load_dwordx4 v[72:75], v1, s[0:1]
	global_load_dwordx4 v[76:79], v1, s[0:1] offset:1024
	s_waitcnt vmcnt(23)
	v_mul_f32_e32 v16, v185, v16
	v_mul_f32_e32 v17, v185, v17
	v_mul_f32_e32 v18, v185, v18
	v_mul_f32_e32 v19, v185, v19
	global_load_dwordx4 v[80:83], v1, s[0:1] offset:2048
	v_mul_f32_e32 v20, v185, v20
	v_mul_f32_e32 v21, v185, v21
	v_mul_f32_e32 v22, v185, v22
	v_mul_f32_e32 v23, v185, v23
	v_lshlrev_b32_e32 v64, 16, v120
	v_and_b32_e32 v65, 0xffff0000, v120
	v_lshlrev_b32_e32 v66, 16, v121
	v_and_b32_e32 v67, 0xffff0000, v121
	v_lshlrev_b32_e32 v68, 16, v122
	v_and_b32_e32 v69, 0xffff0000, v122
	v_lshlrev_b32_e32 v70, 16, v123
	v_and_b32_e32 v71, 0xffff0000, v123
	global_load_dwordx4 v[84:87], v1, s[0:1] offset:3072
	s_waitcnt lgkmcnt(6)
	v_mfma_f32_16x16x32_bf16 v[24:27], v[104:107], v[32:35], 0
	v_mfma_f32_16x16x32_bf16 v[28:31], v[104:107], v[36:39], 0
	global_load_dwordx2 v[88:89], v2, s[2:3]
	s_waitcnt lgkmcnt(4)
	v_mfma_f32_16x16x32_bf16 v[24:27], v[108:111], v[40:43], v[24:27]
	v_mfma_f32_16x16x32_bf16 v[28:31], v[108:111], v[44:47], v[28:31]
	global_load_dwordx2 v[90:91], v2, s[2:3] offset:2048
	s_waitcnt lgkmcnt(2)
	v_mfma_f32_16x16x32_bf16 v[24:27], v[112:115], v[48:51], v[24:27]
	v_mfma_f32_16x16x32_bf16 v[28:31], v[112:115], v[52:55], v[28:31]
	global_load_dwordx4 v[96:99], v1, s[4:5]
	s_waitcnt lgkmcnt(0)
	v_mfma_f32_16x16x32_bf16 v[24:27], v[116:119], v[56:59], v[24:27]
	v_mfma_f32_16x16x32_bf16 v[28:31], v[116:119], v[60:63], v[28:31]
	global_load_dwordx4 v[100:103], v1, s[4:5] offset:1024
	global_load_dword v184, v3, s[6:7]
	global_load_dword v4, v5, s[70:71]
	v_add_u32_e32 v5, v6, v5
	v_add_u32_e32 v1, 0x4000, v1
	v_add_u32_e32 v2, 0x4000, v2
	v_add_u32_e32 v3, 4, v3
	s_nop 2
	v_sub_f32_e32 v64, v64, v24
	v_sub_f32_e32 v65, v65, v25
	v_sub_f32_e32 v66, v66, v26
	v_sub_f32_e32 v67, v67, v27
	v_sub_f32_e32 v68, v68, v28
	v_sub_f32_e32 v69, v69, v29
	v_sub_f32_e32 v70, v70, v30
	v_sub_f32_e32 v71, v71, v31
	v_cvt_pk_bf16_f32 v64, v64, v65
	v_cvt_pk_bf16_f32 v65, v66, v67
	v_cvt_pk_bf16_f32 v68, v68, v69
	v_cvt_pk_bf16_f32 v69, v70, v71
	ds_write_b64 v10, v[64:65] offset:17408
	ds_write_b64 v10, v[68:69] offset:19712
	s_waitcnt lgkmcnt(0)
	s_barrier
	ds_read_b128 v[32:35], v9 offset:17408
	ds_read_b128 v[36:39], v9 offset:19712
	ds_read_b128 v[40:43], v9 offset:17472
	ds_read_b128 v[44:47], v9 offset:19776
	s_waitcnt lgkmcnt(2)
	v_mfma_f32_16x16x32_bf16 v[16:19], v[128:131], v[32:35], v[16:19]
	v_mfma_f32_16x16x32_bf16 v[20:23], v[128:131], v[36:39], v[20:23]
	s_waitcnt lgkmcnt(0)
	v_mfma_f32_16x16x32_bf16 v[16:19], v[132:135], v[40:43], v[16:19]
	v_mfma_f32_16x16x32_bf16 v[20:23], v[132:135], v[44:47], v[20:23]
	s_nop 7
	v_cvt_pk_bf16_f32 v64, v16, v17
	v_cvt_pk_bf16_f32 v65, v18, v19
	v_cvt_pk_bf16_f32 v66, v20, v21
	v_cvt_pk_bf16_f32 v67, v22, v23
	ds_write_b64 v11, v[64:65] offset:0
	ds_write_b64 v11, v[66:67] offset:4352
	s_waitcnt lgkmcnt(0)
	s_barrier
	s_waitcnt vmcnt(26)
	ds_read_b128 v[32:35], v8 offset:0
	ds_read_b128 v[36:39], v8 offset:4352
	ds_read_b128 v[40:43], v8 offset:64
	ds_read_b128 v[44:47], v8 offset:4416
	ds_read_b128 v[48:51], v8 offset:128
	ds_read_b128 v[52:55], v8 offset:4480
	ds_read_b128 v[56:59], v8 offset:192
	ds_read_b128 v[60:63], v8 offset:4544
	global_load_dwordx4 v[104:107], v1, s[0:1]
	global_load_dwordx4 v[108:111], v1, s[0:1] offset:1024
	s_waitcnt vmcnt(23)
	v_mul_f32_e32 v16, v186, v16
	v_mul_f32_e32 v17, v186, v17
	v_mul_f32_e32 v18, v186, v18
	v_mul_f32_e32 v19, v186, v19
	global_load_dwordx4 v[112:115], v1, s[0:1] offset:2048
	v_mul_f32_e32 v20, v186, v20
	v_mul_f32_e32 v21, v186, v21
	v_mul_f32_e32 v22, v186, v22
	v_mul_f32_e32 v23, v186, v23
	v_lshlrev_b32_e32 v64, 16, v188
	v_and_b32_e32 v65, 0xffff0000, v188
	v_lshlrev_b32_e32 v66, 16, v189
	v_and_b32_e32 v67, 0xffff0000, v189
	v_lshlrev_b32_e32 v68, 16, v190
	v_and_b32_e32 v69, 0xffff0000, v190
	v_lshlrev_b32_e32 v70, 16, v191
	v_and_b32_e32 v71, 0xffff0000, v191
	global_load_dwordx4 v[116:119], v1, s[0:1] offset:3072
	s_waitcnt lgkmcnt(6)
	v_mfma_f32_16x16x32_bf16 v[24:27], v[136:139], v[32:35], 0
	v_mfma_f32_16x16x32_bf16 v[28:31], v[136:139], v[36:39], 0
	global_load_dwordx2 v[120:121], v2, s[2:3]
	s_waitcnt lgkmcnt(4)
	v_mfma_f32_16x16x32_bf16 v[24:27], v[140:143], v[40:43], v[24:27]
	v_mfma_f32_16x16x32_bf16 v[28:31], v[140:143], v[44:47], v[28:31]
	global_load_dwordx2 v[122:123], v2, s[2:3] offset:2048
	s_waitcnt lgkmcnt(2)
	v_mfma_f32_16x16x32_bf16 v[24:27], v[144:147], v[48:51], v[24:27]
	v_mfma_f32_16x16x32_bf16 v[28:31], v[144:147], v[52:55], v[28:31]
	global_load_dwordx4 v[128:131], v1, s[4:5]
	s_waitcnt lgkmcnt(0)
	v_mfma_f32_16x16x32_bf16 v[24:27], v[148:151], v[56:59], v[24:27]
	v_mfma_f32_16x16x32_bf16 v[28:31], v[148:151], v[60:63], v[28:31]
	global_load_dwordx4 v[132:135], v1, s[4:5] offset:1024
	global_load_dword v185, v3, s[6:7]
	global_load_dword v4, v5, s[70:71]
	v_add_u32_e32 v5, v6, v5
	v_add_u32_e32 v1, 0x4000, v1
	v_add_u32_e32 v2, 0x4000, v2
	v_add_u32_e32 v3, 4, v3
	s_nop 2
	v_sub_f32_e32 v64, v64, v24
	v_sub_f32_e32 v65, v65, v25
	v_sub_f32_e32 v66, v66, v26
	v_sub_f32_e32 v67, v67, v27
	v_sub_f32_e32 v68, v68, v28
	v_sub_f32_e32 v69, v69, v29
	v_sub_f32_e32 v70, v70, v30
	v_sub_f32_e32 v71, v71, v31
	v_cvt_pk_bf16_f32 v64, v64, v65
	v_cvt_pk_bf16_f32 v65, v66, v67
	v_cvt_pk_bf16_f32 v68, v68, v69
	v_cvt_pk_bf16_f32 v69, v70, v71
	ds_write_b64 v10, v[64:65] offset:17408
	ds_write_b64 v10, v[68:69] offset:19712
	s_waitcnt lgkmcnt(0)
	s_barrier
	ds_read_b128 v[32:35], v9 offset:17408
	ds_read_b128 v[36:39], v9 offset:19712
	ds_read_b128 v[40:43], v9 offset:17472
	ds_read_b128 v[44:47], v9 offset:19776
	s_waitcnt lgkmcnt(2)
	v_mfma_f32_16x16x32_bf16 v[16:19], v[196:199], v[32:35], v[16:19]
	v_mfma_f32_16x16x32_bf16 v[20:23], v[196:199], v[36:39], v[20:23]
	s_waitcnt lgkmcnt(0)
	v_mfma_f32_16x16x32_bf16 v[16:19], v[200:203], v[40:43], v[16:19]
	v_mfma_f32_16x16x32_bf16 v[20:23], v[200:203], v[44:47], v[20:23]
	s_nop 7
	v_cvt_pk_bf16_f32 v64, v16, v17
	v_cvt_pk_bf16_f32 v65, v18, v19
	v_cvt_pk_bf16_f32 v66, v20, v21
	v_cvt_pk_bf16_f32 v67, v22, v23
	ds_write_b64 v11, v[64:65] offset:8704
	ds_write_b64 v11, v[66:67] offset:13056
	s_waitcnt lgkmcnt(0)
	s_barrier
	s_waitcnt vmcnt(26)
	ds_read_b128 v[32:35], v8 offset:8704
	ds_read_b128 v[36:39], v8 offset:13056
	ds_read_b128 v[40:43], v8 offset:8768
	ds_read_b128 v[44:47], v8 offset:13120
	ds_read_b128 v[48:51], v8 offset:8832
	ds_read_b128 v[52:55], v8 offset:13184
	ds_read_b128 v[56:59], v8 offset:8896
	ds_read_b128 v[60:63], v8 offset:13248
	global_load_dwordx4 v[136:139], v1, s[0:1]
	global_load_dwordx4 v[140:143], v1, s[0:1] offset:1024
	s_waitcnt vmcnt(23)
	v_mul_f32_e32 v16, v187, v16
	v_mul_f32_e32 v17, v187, v17
	v_mul_f32_e32 v18, v187, v18
	v_mul_f32_e32 v19, v187, v19
	global_load_dwordx4 v[144:147], v1, s[0:1] offset:2048
	v_mul_f32_e32 v20, v187, v20
	v_mul_f32_e32 v21, v187, v21
	v_mul_f32_e32 v22, v187, v22
	v_mul_f32_e32 v23, v187, v23
	v_lshlrev_b32_e32 v64, 16, v232
	v_and_b32_e32 v65, 0xffff0000, v232
	v_lshlrev_b32_e32 v66, 16, v233
	v_and_b32_e32 v67, 0xffff0000, v233
	v_lshlrev_b32_e32 v68, 16, v234
	v_and_b32_e32 v69, 0xffff0000, v234
	v_lshlrev_b32_e32 v70, 16, v235
	v_and_b32_e32 v71, 0xffff0000, v235
	global_load_dwordx4 v[148:151], v1, s[0:1] offset:3072
	s_waitcnt lgkmcnt(6)
	v_mfma_f32_16x16x32_bf16 v[24:27], v[216:219], v[32:35], 0
	v_mfma_f32_16x16x32_bf16 v[28:31], v[216:219], v[36:39], 0
	global_load_dwordx2 v[188:189], v2, s[2:3]
	s_waitcnt lgkmcnt(4)
	v_mfma_f32_16x16x32_bf16 v[24:27], v[220:223], v[40:43], v[24:27]
	v_mfma_f32_16x16x32_bf16 v[28:31], v[220:223], v[44:47], v[28:31]
	global_load_dwordx2 v[190:191], v2, s[2:3] offset:2048
	s_waitcnt lgkmcnt(2)
	v_mfma_f32_16x16x32_bf16 v[24:27], v[224:227], v[48:51], v[24:27]
	v_mfma_f32_16x16x32_bf16 v[28:31], v[224:227], v[52:55], v[28:31]
	global_load_dwordx4 v[196:199], v1, s[4:5]
	s_waitcnt lgkmcnt(0)
	v_mfma_f32_16x16x32_bf16 v[24:27], v[228:231], v[56:59], v[24:27]
	v_mfma_f32_16x16x32_bf16 v[28:31], v[228:231], v[60:63], v[28:31]
	global_load_dwordx4 v[200:203], v1, s[4:5] offset:1024
	global_load_dword v186, v3, s[6:7]
	global_load_dword v4, v5, s[70:71]
	v_add_u32_e32 v5, v6, v5
	v_add_u32_e32 v1, 0x4000, v1
	v_add_u32_e32 v2, 0x4000, v2
	v_add_u32_e32 v3, 4, v3
	s_nop 2
	v_sub_f32_e32 v64, v64, v24
	v_sub_f32_e32 v65, v65, v25
	v_sub_f32_e32 v66, v66, v26
	v_sub_f32_e32 v67, v67, v27
	v_sub_f32_e32 v68, v68, v28
	v_sub_f32_e32 v69, v69, v29
	v_sub_f32_e32 v70, v70, v30
	v_sub_f32_e32 v71, v71, v31
	v_cvt_pk_bf16_f32 v64, v64, v65
	v_cvt_pk_bf16_f32 v65, v66, v67
	v_cvt_pk_bf16_f32 v68, v68, v69
	v_cvt_pk_bf16_f32 v69, v70, v71
	ds_write_b64 v10, v[64:65] offset:17408
	ds_write_b64 v10, v[68:69] offset:19712
	s_waitcnt lgkmcnt(0)
	s_barrier
	ds_read_b128 v[32:35], v9 offset:17408
	ds_read_b128 v[36:39], v9 offset:19712
	ds_read_b128 v[40:43], v9 offset:17472
	ds_read_b128 v[44:47], v9 offset:19776
	s_waitcnt lgkmcnt(2)
	v_mfma_f32_16x16x32_bf16 v[16:19], v[240:243], v[32:35], v[16:19]
	v_mfma_f32_16x16x32_bf16 v[20:23], v[240:243], v[36:39], v[20:23]
	s_waitcnt lgkmcnt(0)
	v_mfma_f32_16x16x32_bf16 v[16:19], v[244:247], v[40:43], v[16:19]
	v_mfma_f32_16x16x32_bf16 v[20:23], v[244:247], v[44:47], v[20:23]
	s_nop 7
	v_cvt_pk_bf16_f32 v64, v16, v17
	v_cvt_pk_bf16_f32 v65, v18, v19
	v_cvt_pk_bf16_f32 v66, v20, v21
	v_cvt_pk_bf16_f32 v67, v22, v23
	ds_write_b64 v11, v[64:65] offset:0
	ds_write_b64 v11, v[66:67] offset:4352
	s_waitcnt lgkmcnt(0)
	s_barrier
	s_sub_u32 s10, s10, 1
	s_cmp_lg_u32 s10, 0
	s_cbranch_scc1 .Lscan_V_loop
	s_branch .Lscan_done
